# grid barrier release flattened: follower workgroups poll the top-level generation word directly instead of waiting for their XCD leader to republish it (one memory round trip less per barrier); on top
# baseline (speedup 1.0000x reference)
; DI unsigned xb_ld(unsigned* p) { return __hip_atomic_load(p, __ATOMIC_RELAXED, __HIP_MEMORY_SCOPE_AGENT); }
; DI unsigned xb_add(unsigned* p, unsigned v) { return __hip_atomic_fetch_add(p, v, __ATOMIC_RELAXED, __HIP_MEMORY_SCOPE_AGENT); }
; #define XB_SPIN(cond, bar) do { unsigned _sp = 0; while (cond) { __builtin_amdgcn_s_sleep(1); \
;     if ((++_sp & 255u) == 0u) { if (xb_ld(&(bar)[XB_TMO])) break; if (_sp > XB_SPIN_CAP) { atomicAdd(&(bar)[XB_TMO], 1u); break; } } } } while (0)
; DI void xcd_barrier(const XcdBarrier& b) {
;     ...
;     const unsigned old = xb_add(&bar[XB_XSUB(b.x)], 1u);
;     const unsigned gen = old / nloc;
;     if (old + 1u == (gen + 1u) * nloc) {
;       __builtin_amdgcn_fence(__ATOMIC_RELEASE, "agent");
;       asm volatile("s_waitcnt vmcnt(0)" ::: "memory");
;       const unsigned og = xb_add(&bar[XB_TOP], 1u);
;       const unsigned tg = og / nx;
;       if (og + 1u == (tg + 1u) * nx) xb_add(&bar[XB_TOPGEN], 1u);
;       else XB_SPIN(xb_ld(&bar[XB_TOPGEN]) == tg, bar);
;       __builtin_amdgcn_fence(__ATOMIC_ACQUIRE, "agent");
;       xb_add(&bar[XB_XGEN(b.x)], 1u);
;       asm volatile("s_waitcnt vmcnt(0)" ::: "memory");
;     } else {
;       XB_SPIN(xb_ld(&bar[XB_XGEN(b.x)]) == gen, bar);
.LBB0_416:
	s_or_b64 exec, exec, s[26:27]
	v_cvt_f32_u32_e32 v4, v2
	s_waitcnt vmcnt(0)
	v_readfirstlane_b32 s3, v3
	v_sub_u32_e32 v3, 0, v2
	v_rcp_iflag_f32_e32 v4, v4
	v_add_u32_e32 v5, s3, v1
	v_mul_f32_e32 v4, 0x4f7ffffe, v4
	v_cvt_u32_f32_e32 v4, v4
	v_mul_lo_u32 v1, v3, v4
	v_mul_hi_u32 v1, v4, v1
	v_add_u32_e32 v1, v4, v1
	v_mul_hi_u32 v1, v5, v1
	v_mul_lo_u32 v3, v1, v2
	v_sub_u32_e32 v3, v5, v3
	v_add_u32_e32 v4, 1, v1
	v_cmp_ge_u32_e32 vcc, v3, v2
	s_nop 1
	v_cndmask_b32_e32 v1, v1, v4, vcc
	v_sub_u32_e32 v4, v3, v2
	v_cndmask_b32_e32 v3, v3, v4, vcc
	v_add_u32_e32 v4, 1, v1
	v_cmp_ge_u32_e32 vcc, v3, v2
	v_add_u32_e32 v3, 1, v5
	s_nop 0
	v_cndmask_b32_e32 v1, v1, v4, vcc
	v_mul_lo_u32 v4, v2, v1
	v_add_u32_e32 v2, v4, v2
	v_cmp_ne_u32_e32 vcc, v3, v2
	s_and_saveexec_b64 s[4:5], vcc
	s_xor_b64 s[26:27], exec, s[4:5]
	s_cbranch_execz .LBB0_430
	v_readlane_b32 s4, v251, 39
	v_readlane_b32 s5, v251, 40
	s_waitcnt lgkmcnt(0)
	s_nop 3
	global_load_dword v0, v221, s[4:5] sc1
	s_waitcnt vmcnt(0)
	v_cmp_eq_u32_e32 vcc, v0, v1
	s_and_saveexec_b64 s[36:37], vcc
	s_cbranch_execz .LBB0_429
	s_mov_b32 s3, 1
	s_mov_b64 s[38:39], 0
	s_branch .LBB0_420

; DI unsigned xb_ld(unsigned* p) { return __hip_atomic_load(p, __ATOMIC_RELAXED, __HIP_MEMORY_SCOPE_AGENT); }
; #define XB_SPIN(cond, bar) do { unsigned _sp = 0; while (cond) { __builtin_amdgcn_s_sleep(1); \
;     if ((++_sp & 255u) == 0u) { if (xb_ld(&(bar)[XB_TMO])) break; if (_sp > XB_SPIN_CAP) { atomicAdd(&(bar)[XB_TMO], 1u); break; } } } } while (0)
; DI void xcd_barrier(const XcdBarrier& b) {
;     ...
;       XB_SPIN(xb_ld(&bar[XB_XGEN(b.x)]) == gen, bar);
.LBB0_424:
	v_readlane_b32 s4, v251, 39
	v_readlane_b32 s5, v251, 40
	s_add_i32 s3, s3, 1
	s_mov_b64 s[46:47], -1
	s_nop 2
	global_load_dword v0, v221, s[4:5] sc1
	s_waitcnt vmcnt(0)
	v_cmp_ne_u32_e32 vcc, v0, v1
	s_orn2_b64 s[44:45], vcc, exec
	s_branch .LBB0_419

; DI unsigned xb_ld(unsigned* p) { return __hip_atomic_load(p, __ATOMIC_RELAXED, __HIP_MEMORY_SCOPE_AGENT); }
; #define XB_SPIN(cond, bar) do { unsigned _sp = 0; while (cond) { __builtin_amdgcn_s_sleep(1); \
;     if ((++_sp & 255u) == 0u) { if (xb_ld(&(bar)[XB_TMO])) break; if (_sp > XB_SPIN_CAP) { atomicAdd(&(bar)[XB_TMO], 1u); break; } } } } while (0)
; DI void xcd_barrier(const XcdBarrier& b) {
;     ...
;       XB_SPIN(xb_ld(&bar[XB_XGEN(b.x)]) == gen, bar);
.LBB0_993:
	v_readlane_b32 s4, v251, 39
	v_readlane_b32 s5, v251, 40
	s_add_i32 s3, s3, 1
	s_mov_b64 s[44:45], -1
	s_nop 2
	global_load_dword v0, v221, s[4:5] sc1
	s_waitcnt vmcnt(0)
	v_cmp_ne_u32_e32 vcc, v0, v1
	s_orn2_b64 s[42:43], vcc, exec
	s_branch .LBB0_988

; DI unsigned xb_ld(unsigned* p) { return __hip_atomic_load(p, __ATOMIC_RELAXED, __HIP_MEMORY_SCOPE_AGENT); }
; DI unsigned xb_add(unsigned* p, unsigned v) { return __hip_atomic_fetch_add(p, v, __ATOMIC_RELAXED, __HIP_MEMORY_SCOPE_AGENT); }
; #define XB_SPIN(cond, bar) do { unsigned _sp = 0; while (cond) { __builtin_amdgcn_s_sleep(1); \
;     if ((++_sp & 255u) == 0u) { if (xb_ld(&(bar)[XB_TMO])) break; if (_sp > XB_SPIN_CAP) { atomicAdd(&(bar)[XB_TMO], 1u); break; } } } } while (0)
; DI void xcd_barrier(const XcdBarrier& b) {
;     ...
;     const unsigned old = xb_add(&bar[XB_XSUB(b.x)], 1u);
;     const unsigned gen = old / nloc;
;     if (old + 1u == (gen + 1u) * nloc) {
;       __builtin_amdgcn_fence(__ATOMIC_RELEASE, "agent");
;       asm volatile("s_waitcnt vmcnt(0)" ::: "memory");
;       const unsigned og = xb_add(&bar[XB_TOP], 1u);
;       const unsigned tg = og / nx;
;       if (og + 1u == (tg + 1u) * nx) xb_add(&bar[XB_TOPGEN], 1u);
;       else XB_SPIN(xb_ld(&bar[XB_TOPGEN]) == tg, bar);
;       __builtin_amdgcn_fence(__ATOMIC_ACQUIRE, "agent");
;       xb_add(&bar[XB_XGEN(b.x)], 1u);
;       asm volatile("s_waitcnt vmcnt(0)" ::: "memory");
;     } else {
;       XB_SPIN(xb_ld(&bar[XB_XGEN(b.x)]) == gen, bar);
.LBB0_1652:
	s_or_b64 exec, exec, s[36:37]
	v_cvt_f32_u32_e32 v4, v2
	s_waitcnt vmcnt(0)
	v_readfirstlane_b32 s3, v3
	v_sub_u32_e32 v3, 0, v2
	v_rcp_iflag_f32_e32 v4, v4
	v_add_u32_e32 v5, s3, v1
	v_mul_f32_e32 v4, 0x4f7ffffe, v4
	v_cvt_u32_f32_e32 v4, v4
	v_mul_lo_u32 v1, v3, v4
	v_mul_hi_u32 v1, v4, v1
	v_add_u32_e32 v1, v4, v1
	v_mul_hi_u32 v1, v5, v1
	v_mul_lo_u32 v3, v1, v2
	v_sub_u32_e32 v3, v5, v3
	v_add_u32_e32 v4, 1, v1
	v_cmp_ge_u32_e32 vcc, v3, v2
	s_nop 1
	v_cndmask_b32_e32 v1, v1, v4, vcc
	v_sub_u32_e32 v4, v3, v2
	v_cndmask_b32_e32 v3, v3, v4, vcc
	v_add_u32_e32 v4, 1, v1
	v_cmp_ge_u32_e32 vcc, v3, v2
	v_add_u32_e32 v3, 1, v5
	s_nop 0
	v_cndmask_b32_e32 v1, v1, v4, vcc
	v_mul_lo_u32 v4, v2, v1
	v_add_u32_e32 v2, v4, v2
	v_cmp_ne_u32_e32 vcc, v3, v2
	s_and_saveexec_b64 s[4:5], vcc
	s_xor_b64 s[36:37], exec, s[4:5]
	s_cbranch_execz .LBB0_1666
	v_readlane_b32 s4, v251, 39
	v_readlane_b32 s5, v251, 40
	s_waitcnt lgkmcnt(0)
	s_nop 3
	global_load_dword v0, v221, s[4:5] sc1
	s_waitcnt vmcnt(0)
	v_cmp_eq_u32_e32 vcc, v0, v1
	s_and_saveexec_b64 s[40:41], vcc
	s_cbranch_execz .LBB0_1665
	s_mov_b32 s3, 1
	s_mov_b64 s[42:43], 0
	s_branch .LBB0_1656

; DI unsigned xb_ld(unsigned* p) { return __hip_atomic_load(p, __ATOMIC_RELAXED, __HIP_MEMORY_SCOPE_AGENT); }
; #define XB_SPIN(cond, bar) do { unsigned _sp = 0; while (cond) { __builtin_amdgcn_s_sleep(1); \
;     if ((++_sp & 255u) == 0u) { if (xb_ld(&(bar)[XB_TMO])) break; if (_sp > XB_SPIN_CAP) { atomicAdd(&(bar)[XB_TMO], 1u); break; } } } } while (0)
; DI void xcd_barrier(const XcdBarrier& b) {
;     ...
;       XB_SPIN(xb_ld(&bar[XB_XGEN(b.x)]) == gen, bar);
.LBB0_1660:
	v_readlane_b32 s4, v251, 39
	v_readlane_b32 s5, v251, 40
	s_add_i32 s3, s3, 1
	s_mov_b64 s[50:51], -1
	s_nop 2
	global_load_dword v0, v221, s[4:5] sc1
	s_waitcnt vmcnt(0)
	v_cmp_ne_u32_e32 vcc, v0, v1
	s_orn2_b64 s[46:47], vcc, exec
	s_branch .LBB0_1655
